# attention queue: workgroups without a state scan request their first ticket before the P5->P6 grid barrier (atomic round trip hidden behind the barrier); on top of all24
# speedup vs baseline: 1.0014x; 1.0014x over previous
; __device__ __forceinline__ int lane_id_asm() { int l; asm volatile("v_mbcnt_lo_u32_b32 %0, -1, 0\n\tv_mbcnt_hi_u32_b32 %0, -1, %0" : "=v"(l)); return l; }
; __global__ void __launch_bounds__(NWAVES * 64, 2) hybrid_fwd(const Args A) {
;     ...
;             if (F.wave == 0 && lane_id_asm() == 0) misc[0] = atomicAdd(F.ctl + CW_QUEUE + 64 * rep, 1u);
.LBB0_1476:
	s_cmp_gt_u32 s79, 63
	s_cbranch_scc1 .Lq_early_done
	v_readlane_b32 s99, v254, 2
	s_and_b32 s99, s99, 7
	s_cmp_eq_u32 s99, 0
	s_cbranch_scc1 .Lq_early_done
	s_waitcnt lgkmcnt(0)
	s_mov_b64 s[100:101], exec
	s_mov_b64 exec, 1
	v_mov_b32_e32 v240, 1
	v_mov_b32_e32 v241, 0
	global_atomic_add v240, v241, v240, s[86:87] offset:256 sc0
	s_mov_b64 exec, s[100:101]

; __device__ __forceinline__ int lane_id_asm() { int l; asm volatile("v_mbcnt_lo_u32_b32 %0, -1, 0\n\tv_mbcnt_hi_u32_b32 %0, -1, %0" : "=v"(l)); return l; }
; #define LAS __attribute__((address_space(3)))
; __global__ void __launch_bounds__(NWAVES * 64, 2) hybrid_fwd(const Args A) {
;     ...
;         if ((F.vcu & 7) == 0) for (int rs = 0; rs < REPSCAN; ++rs) rwkv_state_scan(F, F.vcu >> 3);
;         LAS unsigned* misc = (LAS unsigned*)(F.lds + L_MISC);
;         const attn_body::bf16* Pd = (const attn_body::bf16*)(F.ws + WS_PDF);
;         for (;;) {
;             if (F.wave == 0 && lane_id_asm() == 0) misc[0] = atomicAdd(F.ctl + CW_QUEUE + 64 * rep, 1u);
;             __syncthreads(); const unsigned idx = misc[0]; __syncthreads();
;             if (idx >= 1024u) break;
.LBB0_1533:
	s_add_u32 s33, s86, 0x9000000
	s_addc_u32 s42, s87, 0
	s_cmp_lt_u32 s79, 64
	s_cselect_b64 s[2:3], -1, 0
	s_lshl_b32 s4, s93, 4
	s_lshl_b32 s43, s93, 5
	s_lshl_b32 s0, s93, 8
	s_and_b32 s44, s4, 48
	s_and_b32 s6, s16, 0x1fffffe0
	s_lshl_b32 s45, s93, 10
	s_cmp_lg_u32 0, -1
	s_cselect_b32 s4, 0, 0
	s_add_i32 s46, s45, s4
	s_add_i32 s48, s0, 0
	s_mul_i32 s0, s93, 0xf00
	s_waitcnt vmcnt(0)
	v_cndmask_b32_e64 v0, 0, 1, s[2:3]
	s_add_i32 s50, 0, 0x25700
	s_mov_b32 s26, 0xfffd0000
	s_add_i32 s47, s46, 0x6000
	s_add_i32 s49, s48, s0
	v_cmp_ne_u32_e64 s[4:5], 1, v0
	v_mov_b32_e32 v1, 0
	v_mov_b32_e32 v206, s50
	s_movk_i32 s51, 0x3ff
	s_movk_i32 s52, 0xc00
	s_lshl_b32 s2, s16, 1
	s_mov_b64 s[10:11], 0x400
	s_lshl_b32 s12, s6, 1
	s_mov_b64 s[14:15], 0x800
	s_mov_b64 s[16:17], 0x30400
	s_mov_b64 s[18:19], 0x60400
	s_mov_b64 s[20:21], 0x90000
	s_mov_b64 s[22:23], 0x30000
	s_mov_b64 s[24:25], 0xf0000
	s_mov_b32 s27, -1
	s_mov_b32 s53, 0x41000000
	s_mov_b64 s[28:29], 0x60000
	s_mov_b64 s[30:31], 0xc0000
	v_mov_b32_e32 v207, 0xff800000
	v_mov_b32_e32 v209, 0x30000
	s_cmp_lg_u64 s[4:5], 0
	s_cbranch_scc1 .Lq_init_done
	v_readlane_b32 s99, v254, 2
	s_and_b32 s99, s99, 7
	s_cmp_lg_u32 s99, 0
	s_cbranch_scc1 .Lq_init_wait
	s_mov_b64 s[100:101], exec
	s_mov_b64 exec, 1
	v_mov_b32_e32 v240, 1
	v_mov_b32_e32 v241, 0
	global_atomic_add v240, v241, v240, s[86:87] offset:256 sc0
	s_mov_b64 exec, s[100:101]
.Lq_init_wait:
	s_waitcnt vmcnt(0)
	v_readfirstlane_b32 s98, v240
